# both dealt prompt-attention key loops at 4 mod 8 bytes
# speedup vs baseline: 1.0010x; 1.0010x over previous
.LBB0_1975:
	s_nop 10
	v_exp_f32_e32 v67, v98
	v_exp_f32_e32 v68, v99
	v_exp_f32_e32 v69, v100
	v_exp_f32_e32 v70, v101
	v_exp_f32_e32 v71, v102
	v_exp_f32_e32 v72, v103
	v_exp_f32_e32 v73, v104
	v_exp_f32_e32 v74, v105
	v_add_f32_e32 v67, 1.0, v67
	v_add_f32_e32 v68, 1.0, v68
	v_add_f32_e32 v69, 1.0, v69
	v_add_f32_e32 v70, 1.0, v70
	v_add_f32_e32 v71, 1.0, v71
	v_add_f32_e32 v72, 1.0, v72
	v_add_f32_e32 v73, 1.0, v73
	v_add_f32_e32 v74, 1.0, v74
	v_log_f32_e32 v67, v67
	v_log_f32_e32 v68, v68
	v_log_f32_e32 v69, v69
	v_log_f32_e32 v70, v70
	v_log_f32_e32 v71, v71
	v_log_f32_e32 v72, v72
	v_log_f32_e32 v73, v73
	v_log_f32_e32 v74, v74
	v_exp_f32_e32 v75, v106
	v_exp_f32_e32 v76, v107
	v_exp_f32_e32 v77, v108
	v_exp_f32_e32 v78, v109
	v_exp_f32_e32 v79, v110
	v_exp_f32_e32 v80, v111
	v_exp_f32_e32 v81, v112
	v_exp_f32_e32 v179, v113
	v_cvt_pk_bf16_f32 v68, v67, v68
	v_cvt_pk_bf16_f32 v69, v69, v70
	v_cvt_pk_bf16_f32 v70, v71, v72
	v_cvt_pk_bf16_f32 v71, v73, v74
	v_mov_b32_e32 v83, v82
	v_mov_b32_e32 v84, v82
	v_mov_b32_e32 v85, v82
	v_mov_b32_e32 v86, v82
	v_mov_b32_e32 v87, v82
	v_mov_b32_e32 v88, v82
	v_mov_b32_e32 v89, v82
	v_mov_b32_e32 v90, v82
	v_mov_b32_e32 v91, v82
	v_mov_b32_e32 v92, v82
	v_mov_b32_e32 v93, v82
	v_mov_b32_e32 v94, v82
	v_mov_b32_e32 v95, v82
	v_mov_b32_e32 v96, v82
	v_mov_b32_e32 v97, v82
	v_add_f32_e32 v75, 1.0, v75
	v_add_f32_e32 v76, 1.0, v76
	v_mfma_f32_32x32x16_bf16 v[82:97], v[152:155], v[68:71], v[82:97]
	v_add_f32_e32 v77, 1.0, v77
	v_add_f32_e32 v78, 1.0, v78
	v_add_f32_e32 v79, 1.0, v79
	v_add_f32_e32 v80, 1.0, v80
	v_add_f32_e32 v81, 1.0, v81
	v_add_f32_e32 v68, 1.0, v179
	v_log_f32_e32 v75, v75
	v_log_f32_e32 v76, v76
	v_log_f32_e32 v77, v77
	v_log_f32_e32 v78, v78
	v_log_f32_e32 v79, v79
	v_log_f32_e32 v80, v80
	v_log_f32_e32 v67, v81
	v_log_f32_e32 v71, v68
	v_cvt_pk_bf16_f32 v68, v75, v76
	v_cvt_pk_bf16_f32 v69, v77, v78
	v_cvt_pk_bf16_f32 v70, v79, v80
	v_cvt_pk_bf16_f32 v71, v67, v71
	s_andn2_b64 vcc, exec, s[72:73]
	s_nop 0
	v_mfma_f32_32x32x16_bf16 v[82:97], v[148:151], v[68:71], v[82:97]
	s_nop 11
	v_sub_f32_e32 v68, v99, v83
	v_exp_f32_e32 v72, v68
	v_sub_f32_e32 v68, v100, v84
	v_exp_f32_e32 v73, v68
	v_sub_f32_e32 v68, v101, v85
	v_exp_f32_e32 v74, v68
	v_sub_f32_e32 v68, v102, v86
	v_exp_f32_e32 v75, v68
	v_sub_f32_e32 v68, v103, v87
	v_exp_f32_e32 v76, v68
	v_sub_f32_e32 v68, v104, v88
	v_exp_f32_e32 v77, v68
	v_sub_f32_e32 v68, v105, v89
	v_exp_f32_e32 v78, v68
	v_sub_f32_e32 v68, v106, v90
	v_exp_f32_e32 v80, v68
	v_sub_f32_e32 v68, v107, v91
	v_exp_f32_e32 v81, v68
	v_sub_f32_e32 v68, v108, v92
	v_exp_f32_e32 v83, v68
	v_sub_f32_e32 v68, v109, v93
	v_exp_f32_e32 v88, v68
	v_sub_f32_e32 v68, v110, v94
	v_exp_f32_e32 v89, v68
	v_sub_f32_e32 v68, v111, v95
	v_exp_f32_e32 v90, v68
	v_sub_f32_e32 v68, v112, v96
	v_exp_f32_e32 v91, v68
	v_xor_b32_e32 v68, v167, v174
	v_lshl_add_u32 v92, v68, 4, v177
	ds_read_b128 v[68:71], v92 offset:16384
	v_sub_f32_e32 v67, v98, v82
	v_exp_f32_e32 v67, v67
	v_cvt_pk_bf16_f32 v73, v73, v74
	v_cvt_pk_bf16_f32 v74, v75, v76
	v_cvt_pk_bf16_f32 v75, v77, v78
	v_cvt_pk_bf16_f32 v72, v67, v72
	v_xor_b32_e32 v67, v178, v167
	v_lshl_add_u32 v67, v67, 4, v177
	s_waitcnt lgkmcnt(0)
	v_mfma_f32_32x32x16_bf16 v[50:65], v[68:71], v[72:75], v[50:65]
	v_sub_f32_e32 v68, v113, v97
	ds_read_b128 v[76:79], v67 offset:16384
	ds_read_b128 v[84:87], v92 offset:20480
	v_exp_f32_e32 v71, v68
	v_cvt_pk_bf16_f32 v68, v80, v81
	v_cvt_pk_bf16_f32 v69, v83, v88
	v_cvt_pk_bf16_f32 v70, v89, v90
	v_cvt_pk_bf16_f32 v71, v91, v71
	ds_read_b128 v[88:91], v67 offset:20480
	s_waitcnt lgkmcnt(1)
	v_mfma_f32_32x32x16_bf16 v[34:49], v[84:87], v[72:75], v[34:49]
	v_mfma_f32_32x32x16_bf16 v[50:65], v[76:79], v[68:71], v[50:65]
	ds_read_b128 v[76:79], v92 offset:24576
	ds_read_b128 v[84:87], v92 offset:28672
	s_waitcnt lgkmcnt(1)
	v_mfma_f32_32x32x16_bf16 v[18:33], v[76:79], v[72:75], v[18:33]
	s_waitcnt lgkmcnt(0)
	v_mfma_f32_32x32x16_bf16 v[2:17], v[84:87], v[72:75], v[2:17]
	v_mfma_f32_32x32x16_bf16 v[34:49], v[88:91], v[68:71], v[34:49]
	ds_read_b128 v[76:79], v67 offset:24576
	ds_read_b128 v[88:91], v67 offset:28672
	v_and_or_b32 v67, v223, 64, v175
	v_lshlrev_b32_e32 v177, 2, v67
	ds_bpermute_b32 v67, v177, v82
	s_waitcnt lgkmcnt(2)
	v_mfma_f32_32x32x16_bf16 v[18:33], v[76:79], v[68:71], v[18:33]
	s_waitcnt lgkmcnt(1)
	v_mfma_f32_32x32x16_bf16 v[2:17], v[88:91], v[68:71], v[2:17]
	s_cbranch_vccnz .LBB0_1958
	s_sub_i32 s40, 0x7e, s46
	s_lshl_b32 s41, s40, 15
	v_bitop3_b32 v68, v174, v176, 1 bitop3:0x78
	s_and_b32 s41, s41, 0x18000
	v_lshl_add_u32 v176, v68, 4, v115
	s_add_i32 s41, s41, 0
	v_add_u32_e32 v93, s41, v176
	v_lshlrev_b32_e32 v178, 5, v167
	v_add_u32_e32 v68, v93, v178
	ds_read_b128 v[68:71], v68 offset:8192
	v_xor_b32_e32 v179, 32, v178
	v_add_u32_e32 v72, v93, v179
	ds_read_b128 v[84:87], v72 offset:8192
	v_xor_b32_e32 v180, 64, v178
	v_add_u32_e32 v88, v93, v180
	s_waitcnt lgkmcnt(1)
	v_mfma_f32_32x32x16_bf16 v[68:83], v[68:71], v[116:119], 0
	ds_read_b128 v[88:91], v88 offset:8192
	v_xor_b32_e32 v181, 0x60, v178
	v_xor_b32_e32 v182, 0x80, v178
	v_xor_b32_e32 v183, 0xa0, v178
	v_xor_b32_e32 v186, 0xc0, v178
	v_sub_f32_e32 v92, v67, v66
	v_lshrrev_b32_e32 v67, 1, v175
	s_waitcnt lgkmcnt(1)
	v_mfma_f32_32x32x16_bf16 v[68:83], v[84:87], v[120:123], v[68:83]
	v_add_u32_e32 v84, v93, v181
	ds_read_b128 v[84:87], v84 offset:8192
	v_xor_b32_e32 v187, 0xe0, v178
	v_bitop3_b32 v110, v67, v174, 1 bitop3:0x6c
	v_add_u32_e32 v67, v93, v187
	v_exp_f32_e32 v184, v66
	v_cndmask_b32_e64 v94, v171, 0, s[8:9]
	s_waitcnt lgkmcnt(1)
	v_mfma_f32_32x32x16_bf16 v[68:83], v[88:91], v[124:127], v[68:83]
	v_add_u32_e32 v88, v93, v182
	ds_read_b128 v[88:91], v88 offset:8192
	v_cndmask_b32_e64 v95, v171, 0, s[14:15]
	v_cndmask_b32_e64 v96, v171, 0, s[6:7]
	v_cndmask_b32_e64 v97, v171, 0, s[10:11]
	v_cndmask_b32_e64 v98, v171, 0, s[16:17]
	v_cndmask_b32_e64 v99, v171, 0, s[22:23]
	s_waitcnt lgkmcnt(1)
	v_mfma_f32_32x32x16_bf16 v[68:83], v[84:87], v[128:131], v[68:83]
	v_add_u32_e32 v84, v93, v183
	ds_read_b128 v[84:87], v84 offset:8192
	v_cndmask_b32_e64 v100, v171, 0, s[12:13]
	v_cndmask_b32_e64 v101, v171, 0, s[18:19]
	v_cndmask_b32_e64 v102, v171, 0, s[24:25]
	v_cndmask_b32_e64 v103, v171, 0, s[30:31]
	v_cndmask_b32_e64 v104, v171, 0, s[20:21]
	s_waitcnt lgkmcnt(1)
	v_mfma_f32_32x32x16_bf16 v[68:83], v[88:91], v[132:135], v[68:83]
	v_add_u32_e32 v88, v93, v186
	ds_read_b128 v[88:91], v88 offset:8192
	v_cndmask_b32_e64 v105, v171, 0, s[26:27]
	v_cndmask_b32_e64 v106, v171, 0, s[34:35]
	v_cndmask_b32_e64 v107, v171, 0, s[38:39]
	v_cndmask_b32_e64 v108, v171, 0, s[28:29]
	v_cndmask_b32_e64 v109, v171, 0, s[36:37]
	s_waitcnt lgkmcnt(1)
	v_mfma_f32_32x32x16_bf16 v[68:83], v[84:87], v[136:139], v[68:83]
	ds_read_b128 v[84:87], v67 offset:8192
	v_lshlrev_b32_e32 v66, 3, v175
	v_mov_b32_e32 v115, v157
	v_mov_b32_e32 v167, v157
	v_lshl_add_u32 v190, v110, 4, v163
	s_lshl_b32 s6, s46, 15
	s_lshl_b32 s7, s46, 6
	s_waitcnt lgkmcnt(1)
	v_mfma_f32_32x32x16_bf16 v[68:83], v[88:91], v[140:143], v[68:83]
	v_and_b32_e32 v185, 0x60, v66
	v_bitop3_b32 v174, v66, 32, v172 bitop3:0x6c
	v_bitop3_b32 v188, v66, 64, v172 bitop3:0x6c
	v_bitop3_b32 v189, v66, s76, v66 bitop3:0xc
	v_lshl_add_u64 v[66:67], s[60:61], 0, v[114:115]
	v_lshl_add_u64 v[166:167], s[60:61], 0, v[166:167]
	v_perm_b32 v151, v101, v100, s75
	s_waitcnt lgkmcnt(0)
	v_mfma_f32_32x32x16_bf16 v[68:83], v[84:87], v[144:147], v[68:83]
	v_mov_b32_e32 v84, 0
	v_perm_b32 v150, v99, v98, s75
	v_add_u32_e32 v175, 0, v190
	v_perm_b32 v149, v97, v96, s75
	v_perm_b32 v148, v95, v94, s75
	v_perm_b32 v155, v109, v108, s75
	v_perm_b32 v154, v107, v106, s75
	v_perm_b32 v153, v105, v104, s75
	v_perm_b32 v152, v103, v102, s75
	v_add_u32_e32 v191, 0, v176
	s_sub_i32 s6, 0x3e0000, s6
	s_sub_i32 s7, 0, s7
	v_mov_b32_e32 v85, v84
	v_mov_b32_e32 v86, v84
	v_mov_b32_e32 v87, v84
	v_mov_b32_e32 v88, v84
	v_mov_b32_e32 v89, v84
	v_mov_b32_e32 v90, v84
	v_mov_b32_e32 v91, v84
	s_branch .LBB0_1978
	.p2align 3
	s_nop 0
